# attention PV section: group-wide lgkmcnt(0) replaced by exact counted waits per MFMA (over v31)
# speedup vs baseline: 1.0071x; 1.0055x over previous
; __device__ __forceinline__ void finishSM(f32x16& p0, f32x16& p1, float alpha, float& l_reg, bf16x8& pa0, bf16x8& pa1, bf16x8& pa2, bf16x8& pa3) {
;   for (int r = 0; r < 16; ++r) p1[r] = __builtin_amdgcn_exp2f(p1[r]);
;   float ps = 0; for (int r = 0; r < 16; ++r) ps += p0[r]; for (int r = 0; r < 16; ++r) ps += p1[r];
;   { auto rr = __builtin_amdgcn_permlane32_swap(__float_as_uint(ps), __float_as_uint(ps), false, false);
;     ps = __uint_as_float(rr[0]) + __uint_as_float(rr[1]); }
;   l_reg = l_reg * alpha + ps;
;     ...
;   PK4(p0, 0, pa0); PK4(p0, 8, pa1); PK4(p1, 0, pa2); PK4(p1, 8, pa3);
;     ...
; }
; __device__ __forceinline__ void qkt(f32x16& p0, f32x16& p1, const bf16* Ks, const bf16x8* qr, int r32, int hi) {
;   p0 = f32x16{}; p1 = f32x16{};
;   for (int d0 = 0; d0 < 8; ++d0) { int cb = (d0 * 16 + hi * 8) * 2;
;     bf16x8 b0 = *reinterpret_cast<const bf16x8*>((const char*)Ks + KSWZ(r32, cb));
;     bf16x8 b1 = *reinterpret_cast<const bf16x8*>((const char*)Ks + KSWZ(32 + r32, cb));
;     p0 = __builtin_amdgcn_mfma_f32_32x32x16_bf16(b0, qr[d0], p0, 0, 0, 0);
;     p1 = __builtin_amdgcn_mfma_f32_32x32x16_bf16(b1, qr[d0], p1, 0, 0, 0); }
.LBB0_180:
	ds_read_b128 v[66:69], v212 offset:49152
	ds_read_b128 v[70:73], v212 offset:57344
	ds_read_b128 v[228:231], v217 offset:49152
	ds_read_b128 v[232:235], v217 offset:57344
	v_add_f32_e32 v162, 0, v163
	v_add_f32_e32 v162, v177, v162
	s_waitcnt lgkmcnt(3)
	v_mfma_f32_32x32x16_bf16 v[82:97], v[66:69], v[118:121], 0
	v_add_f32_e32 v162, v164, v162
	v_add_f32_e32 v162, v224, v162
	v_add_f32_e32 v162, v176, v162
	v_add_f32_e32 v162, v227, v162
	v_add_f32_e32 v162, v165, v162
	v_add_f32_e32 v162, v175, v162
	v_add_f32_e32 v162, v166, v162
	s_waitcnt lgkmcnt(2)
	v_mfma_f32_32x32x16_bf16 v[66:81], v[70:73], v[118:121], 0
	v_add_f32_e32 v162, v173, v162
	v_add_f32_e32 v162, v167, v162
	v_add_f32_e32 v162, v174, v162
	v_exp_f32_e32 v160, v160
	v_add_f32_e32 v162, v168, v162
	v_exp_f32_e32 v161, v161
	v_add_f32_e32 v162, v171, v162
	s_waitcnt lgkmcnt(1)
	v_mfma_f32_32x32x16_bf16 v[82:97], v[228:231], v[110:113], v[82:97]
	v_exp_f32_e32 v158, v158
	v_add_f32_e32 v162, v169, v162
	v_exp_f32_e32 v159, v159
	v_add_f32_e32 v162, v172, v162
	v_exp_f32_e32 v154, v154
	v_add_f32_e32 v162, v160, v162
	v_exp_f32_e32 v155, v155
	s_waitcnt lgkmcnt(0)
	v_mfma_f32_32x32x16_bf16 v[66:81], v[232:235], v[110:113], v[66:81]
	ds_read_b128 v[228:231], v216 offset:49152
	ds_read_b128 v[232:235], v216 offset:57344
	v_add_f32_e32 v162, v161, v162
	v_exp_f32_e32 v150, v150
	v_add_f32_e32 v162, v158, v162
	v_exp_f32_e32 v151, v151
	v_add_f32_e32 v162, v159, v162
	v_exp_f32_e32 v148, v148
	s_waitcnt lgkmcnt(1)
	v_mfma_f32_32x32x16_bf16 v[82:97], v[228:231], v[126:129], v[82:97]
	v_add_f32_e32 v162, v154, v162
	v_exp_f32_e32 v149, v149
	v_add_f32_e32 v162, v155, v162
	v_exp_f32_e32 v156, v156
	v_add_f32_e32 v162, v150, v162
	v_exp_f32_e32 v157, v157
	v_add_f32_e32 v162, v151, v162
	s_waitcnt lgkmcnt(0)
	v_mfma_f32_32x32x16_bf16 v[66:81], v[232:235], v[126:129], v[66:81]
	ds_read_b128 v[228:231], v215 offset:49152
	ds_read_b128 v[232:235], v215 offset:57344
	v_exp_f32_e32 v152, v152
	v_add_f32_e32 v162, v148, v162
	v_exp_f32_e32 v153, v153
	v_add_f32_e32 v162, v149, v162
	v_exp_f32_e32 v146, v146
	v_add_f32_e32 v162, v156, v162
	s_waitcnt lgkmcnt(1)
	v_mfma_f32_32x32x16_bf16 v[82:97], v[228:231], v[122:125], v[82:97]
	v_exp_f32_e32 v147, v147
	v_add_f32_e32 v162, v157, v162
	v_add_f32_e32 v162, v152, v162
	v_add_f32_e32 v162, v153, v162
	v_add_f32_e32 v162, v146, v162
	v_add_f32_e32 v221, v147, v162
	v_mov_b32_e32 v222, v221
	s_waitcnt lgkmcnt(0)
	v_mfma_f32_32x32x16_bf16 v[66:81], v[232:235], v[122:125], v[66:81]
	ds_read_b128 v[228:231], v213 offset:49152
	ds_read_b128 v[232:235], v213 offset:57344
	v_permlane32_swap_b32_e32 v221, v222
	s_waitcnt lgkmcnt(1)
	v_mfma_f32_32x32x16_bf16 v[82:97], v[228:231], v[114:117], v[82:97]
	s_waitcnt lgkmcnt(0)
	v_mfma_f32_32x32x16_bf16 v[66:81], v[232:235], v[114:117], v[66:81]
	ds_read_b128 v[228:231], v214 offset:49152
	ds_read_b128 v[232:235], v214 offset:57344
	s_waitcnt lgkmcnt(1)
	v_mfma_f32_32x32x16_bf16 v[82:97], v[228:231], v[106:109], v[82:97]
	s_waitcnt lgkmcnt(0)
	v_mfma_f32_32x32x16_bf16 v[66:81], v[232:235], v[106:109], v[66:81]
	ds_read_b128 v[228:231], v219 offset:49152
	ds_read_b128 v[232:235], v219 offset:57344
	s_waitcnt lgkmcnt(1)
	v_mfma_f32_32x32x16_bf16 v[82:97], v[228:231], v[102:105], v[82:97]
	s_waitcnt lgkmcnt(0)
	v_mfma_f32_32x32x16_bf16 v[66:81], v[232:235], v[102:105], v[66:81]
	ds_read_b128 v[228:231], v218 offset:49152
	ds_read_b128 v[232:235], v218 offset:57344
	v_cvt_pk_bf16_f32 v162, v163, v177
	v_cvt_pk_bf16_f32 v163, v164, v224
	v_cvt_pk_bf16_f32 v164, v176, v227
	v_cvt_pk_bf16_f32 v165, v165, v175
	v_cvt_pk_bf16_f32 v166, v166, v173
	v_cvt_pk_bf16_f32 v167, v167, v174
	s_waitcnt lgkmcnt(1)
	v_mfma_f32_32x32x16_bf16 v[82:97], v[228:231], v[98:101], v[82:97]
	v_permlane32_swap_b32_e32 v162, v164
	v_cvt_pk_bf16_f32 v168, v168, v171
	v_cvt_pk_bf16_f32 v169, v169, v172
	v_cvt_pk_bf16_f32 v172, v160, v161
	v_cvt_pk_bf16_f32 v173, v158, v159
	v_cvt_pk_bf16_f32 v174, v154, v155
	s_waitcnt lgkmcnt(0)
	v_mfma_f32_32x32x16_bf16 v[66:81], v[232:235], v[98:101], v[66:81]
	v_cvt_pk_bf16_f32 v175, v150, v151
	v_cvt_pk_bf16_f32 v224, v148, v149
	v_cvt_pk_bf16_f32 v225, v156, v157
	v_cvt_pk_bf16_f32 v226, v152, v153
	v_cvt_pk_bf16_f32 v227, v146, v147
	v_permlane32_swap_b32_e32 v163, v165
	v_permlane32_swap_b32_e32 v166, v168
	v_permlane32_swap_b32_e32 v167, v169
	v_permlane32_swap_b32_e32 v172, v174
	v_permlane32_swap_b32_e32 v173, v175
	v_permlane32_swap_b32_e32 v224, v226
	v_permlane32_swap_b32_e32 v225, v227
	s_movk_i32 s0, 0xa000
	v_add_co_u32_e32 v146, vcc, s0, v182
	s_movk_i32 s0, 0xc000
	s_nop 0
	v_addc_co_u32_e32 v147, vcc, -1, v183, vcc
	v_add_co_u32_e32 v150, vcc, s0, v182
	s_mov_b32 s0, 0xfeefa000
	s_nop 0
	v_addc_co_u32_e32 v151, vcc, -1, v183, vcc
	v_add_co_u32_e32 v154, vcc, s0, v182
	s_mov_b32 s0, 0xfeefc000
	s_nop 0
	v_addc_co_u32_e32 v155, vcc, -1, v183, vcc
	v_add_co_u32_e32 v158, vcc, s0, v182
	global_load_dwordx4 v[146:149], v[146:147], off
	s_nop 0
	global_load_dwordx4 v[150:153], v[150:151], off
	v_addc_co_u32_e32 v159, vcc, -1, v183, vcc
	global_load_dwordx4 v[154:157], v[154:155], off
	s_nop 0
	global_load_dwordx4 v[158:161], v[158:159], off
	ds_read_b64_tr_b16 v[228:229], v207 offset:0
	ds_read_b64_tr_b16 v[230:231], v207 offset:0x800
	ds_read_b64_tr_b16 v[232:233], v207 offset:0x1000
	ds_read_b64_tr_b16 v[234:235], v207 offset:0x1800
	ds_read_b64_tr_b16 v[236:237], v207 offset:0x2000
	ds_read_b64_tr_b16 v[238:239], v207 offset:0x2800
	ds_read_b64_tr_b16 v[240:241], v207 offset:0x3000
	ds_read_b64_tr_b16 v[242:243], v207 offset:0x3800
	s_nop 0
	s_waitcnt lgkmcnt(6)
; #define SBAR() __builtin_amdgcn_sched_barrier(0)
; __device__ __forceinline__ void partialSM(f32x16& p0, f32x16& p1, float& m_reg, float& mn, float& alpha) {
;     ...
;   float pmax = p0[0]; for (int r = 1; r < 16; ++r) pmax = fmaxf(pmax, p0[r]); for (int r = 0; r < 16; ++r) pmax = fmaxf(pmax, p1[r]);
;   { auto rr = __builtin_amdgcn_permlane32_swap(__float_as_uint(pmax), __float_as_uint(pmax), false, false);
;     pmax = fmaxf(__uint_as_float(rr[0]), __uint_as_float(rr[1])); }
;   if (__builtin_expect(__all(pmax - m_reg <= THR / SCALE), 1)) { mn = m_reg; alpha = 1.f; }
;   else { mn = fmaxf(m_reg, pmax); alpha = __builtin_amdgcn_exp2f((m_reg - mn) * C); m_reg = mn; }
; template <int OFF> __device__ __forceinline__ s16x4 tr_read(int vb) {
;   s16x4 r; asm volatile("ds_read_b64_tr_b16 %0, %1 offset:%2" : "=&v"(r) : "v"(vb), "i"(OFF) : "memory"); return r;
; }
; template <int D0> __device__ __forceinline__ void pv_one(f32x16& od, int vb, bf16x8 pa0, bf16x8 pa1, bf16x8 pa2, bf16x8 pa3) {
;   const s16x4 l0 = tr_read<v_rd_off(D0, 0, 0)>(vb), h0 = tr_read<v_rd_off(D0, 0, 1)>(vb), l1 = tr_read<v_rd_off(D0, 1, 0)>(vb), h1 = tr_read<v_rd_off(D0, 1, 1)>(vb);
;   const s16x4 l2 = tr_read<v_rd_off(D0, 2, 0)>(vb), h2 = tr_read<v_rd_off(D0, 2, 1)>(vb), l3 = tr_read<v_rd_off(D0, 3, 0)>(vb), h3 = tr_read<v_rd_off(D0, 3, 1)>(vb);
;   asm volatile("s_waitcnt lgkmcnt(0)" ::: "memory"); SBAR();
;     ...
;   od = __builtin_amdgcn_mfma_f32_32x32x16_bf16(pa0, PK(l0, h0), od, 0, 0, 0);
;   od = __builtin_amdgcn_mfma_f32_32x32x16_bf16(pa1, PK(l1, h1), od, 0, 0, 0);
;   od = __builtin_amdgcn_mfma_f32_32x32x16_bf16(pa2, PK(l2, h2), od, 0, 0, 0);
;   od = __builtin_amdgcn_mfma_f32_32x32x16_bf16(pa3, PK(l3, h3), od, 0, 0, 0);
;     ...
; }
; __device__ __forceinline__ void pv_d0(f32x16* o, int vb, bf16x8 pa0, bf16x8 pa1, bf16x8 pa2, bf16x8 pa3) {
;   pv_one<0>(o[0], vb, pa0, pa1, pa2, pa3); pv_one<1>(o[1], vb, pa0, pa1, pa2, pa3); pv_one<2>(o[2], vb, pa0, pa1, pa2, pa3); pv_one<3>(o[3], vb, pa0, pa1, pa2, pa3);
	v_mfma_f32_32x32x16_bf16 v[2:17], v[162:165], v[228:231], v[2:17]
	ds_read_b64_tr_b16 v[228:229], v207 offset:0x200
	ds_read_b64_tr_b16 v[230:231], v207 offset:0xa00
	s_waitcnt lgkmcnt(6)
	v_mfma_f32_32x32x16_bf16 v[2:17], v[166:169], v[232:235], v[2:17]
	ds_read_b64_tr_b16 v[232:233], v207 offset:0x1200
	ds_read_b64_tr_b16 v[234:235], v207 offset:0x1a00
	s_waitcnt lgkmcnt(6)
	v_mfma_f32_32x32x16_bf16 v[2:17], v[172:175], v[236:239], v[2:17]
	ds_read_b64_tr_b16 v[236:237], v207 offset:0x2200
	ds_read_b64_tr_b16 v[238:239], v207 offset:0x2a00
	s_waitcnt lgkmcnt(6)
	v_mfma_f32_32x32x16_bf16 v[2:17], v[224:227], v[240:243], v[2:17]
	ds_read_b64_tr_b16 v[240:241], v207 offset:0x3200
	ds_read_b64_tr_b16 v[242:243], v207 offset:0x3a00
	s_waitcnt lgkmcnt(6)
	v_mfma_f32_32x32x16_bf16 v[50:65], v[162:165], v[228:231], v[50:65]
	ds_read_b64_tr_b16 v[228:229], v207 offset:0x400
	ds_read_b64_tr_b16 v[230:231], v207 offset:0xc00
	s_waitcnt lgkmcnt(6)
	v_mfma_f32_32x32x16_bf16 v[50:65], v[166:169], v[232:235], v[50:65]
	ds_read_b64_tr_b16 v[232:233], v207 offset:0x1400
	ds_read_b64_tr_b16 v[234:235], v207 offset:0x1c00
	s_waitcnt lgkmcnt(6)
	v_mfma_f32_32x32x16_bf16 v[50:65], v[172:175], v[236:239], v[50:65]
	ds_read_b64_tr_b16 v[236:237], v207 offset:0x2400
	ds_read_b64_tr_b16 v[238:239], v207 offset:0x2c00
	s_waitcnt lgkmcnt(6)
	v_mfma_f32_32x32x16_bf16 v[50:65], v[224:227], v[240:243], v[50:65]
	ds_read_b64_tr_b16 v[240:241], v207 offset:0x3400
	ds_read_b64_tr_b16 v[242:243], v207 offset:0x3c00
	s_waitcnt lgkmcnt(6)
	v_mfma_f32_32x32x16_bf16 v[34:49], v[162:165], v[228:231], v[34:49]
	ds_read_b64_tr_b16 v[228:229], v207 offset:0x600
	ds_read_b64_tr_b16 v[230:231], v207 offset:0xe00
	s_waitcnt lgkmcnt(6)
	v_mfma_f32_32x32x16_bf16 v[34:49], v[166:169], v[232:235], v[34:49]
	ds_read_b64_tr_b16 v[232:233], v207 offset:0x1600
	ds_read_b64_tr_b16 v[234:235], v207 offset:0x1e00
	s_waitcnt lgkmcnt(6)
	v_mfma_f32_32x32x16_bf16 v[34:49], v[172:175], v[236:239], v[34:49]
	ds_read_b64_tr_b16 v[236:237], v207 offset:0x2600
	ds_read_b64_tr_b16 v[238:239], v207 offset:0x2e00
	s_waitcnt lgkmcnt(6)
	v_mfma_f32_32x32x16_bf16 v[34:49], v[224:227], v[240:243], v[34:49]
	ds_read_b64_tr_b16 v[240:241], v207 offset:0x3600
	ds_read_b64_tr_b16 v[242:243], v207 offset:0x3e00
	s_waitcnt lgkmcnt(6)
	v_mfma_f32_32x32x16_bf16 v[18:33], v[162:165], v[228:231], v[18:33]
	v_max_f32_e32 v162, v83, v83
	v_max_f32_e32 v163, v82, v82
	v_max_f32_e32 v162, v163, v162
	v_max3_f32 v162, v162, v84, v85
	v_max3_f32 v162, v162, v86, v87
	v_max3_f32 v162, v162, v88, v89
	v_max3_f32 v162, v162, v90, v91
	v_max3_f32 v162, v162, v92, v93
	v_max3_f32 v162, v162, v94, v95
	s_waitcnt lgkmcnt(4)
	v_mfma_f32_32x32x16_bf16 v[18:33], v[166:169], v[232:235], v[18:33]
	v_max3_f32 v162, v162, v96, v97
	v_max3_f32 v162, v162, v66, v67
	v_max3_f32 v162, v162, v68, v69
	v_max3_f32 v162, v162, v70, v71
	v_max3_f32 v162, v162, v72, v73
	v_max3_f32 v162, v162, v74, v75
	v_max3_f32 v162, v162, v76, v77
	v_max3_f32 v162, v162, v78, v79
	s_waitcnt lgkmcnt(2)
	v_mfma_f32_32x32x16_bf16 v[18:33], v[172:175], v[236:239], v[18:33]
	v_max3_f32 v162, v162, v80, v81
	v_mov_b32_e32 v163, v162
	s_nop 1
	v_permlane32_swap_b32_e32 v162, v163
	v_max_f32_e32 v163, v163, v163
	v_max_f32_e32 v162, v162, v162
	v_max_f32_e32 v162, v162, v163
	v_sub_f32_e32 v163, v162, v170
	v_cmp_ge_f32_e32 vcc, s27, v163
	v_max_f32_e32 v163, v170, v170
	v_max_f32_e32 v162, v163, v162
	s_waitcnt lgkmcnt(0)
	v_mfma_f32_32x32x16_bf16 v[18:33], v[224:227], v[240:243], v[18:33]
	v_sub_f32_e32 v163, v170, v162
	v_mul_f32_e32 v163, 0x3e0293ee, v163
	v_exp_f32_e32 v163, v163
	s_cmp_eq_u64 vcc, exec
	s_cselect_b64 s[0:1], -1, 0
	s_barrier
	s_waitcnt vmcnt(4)
	v_cndmask_b32_e64 v223, v163, 1.0, s[0:1]
	v_cmp_gt_f32_e32 vcc, 1.0, v223
	s_waitcnt vmcnt(7)
	ds_write_b128 v210, v[130:133]
	s_waitcnt vmcnt(6)
	ds_write_b128 v211, v[138:141]
	s_waitcnt vmcnt(5)
	ds_write_b128 v208, v[134:137] offset:32768
	s_waitcnt vmcnt(4)
	ds_write_b128 v209, v[142:145] offset:32768
	s_cbranch_vccz .LBB0_184
	s_and_saveexec_b64 s[44:45], s[40:41]
	ds_write_b32 v185, v223 offset:128
	s_or_b64 exec, exec, s[44:45]
	s_waitcnt lgkmcnt(0)
	v_add_u32_e32 v163, v181, v0
	ds_read_b128 v[164:167], v163 offset:224
	ds_read_b128 v[172:175], v163 offset:192
	ds_read_b128 v[224:227], v163 offset:160
	ds_read_b128 v[228:231], v163 offset:128
	s_waitcnt lgkmcnt(3)
	v_pk_mul_f32 v[14:15], v[14:15], v[164:165]
	s_waitcnt lgkmcnt(2)
	v_pk_mul_f32 v[10:11], v[10:11], v[172:173]
	s_waitcnt lgkmcnt(1)
	v_pk_mul_f32 v[6:7], v[6:7], v[224:225]
	v_pk_mul_f32 v[16:17], v[16:17], v[166:167]
	v_pk_mul_f32 v[12:13], v[12:13], v[174:175]
	v_pk_mul_f32 v[8:9], v[8:9], v[226:227]
	s_waitcnt lgkmcnt(0)
	v_pk_mul_f32 v[4:5], v[4:5], v[230:231]
	v_pk_mul_f32 v[2:3], v[2:3], v[228:229]
	v_pk_mul_f32 v[62:63], v[62:63], v[164:165]
	v_pk_mul_f32 v[58:59], v[58:59], v[172:173]
	v_pk_mul_f32 v[54:55], v[54:55], v[224:225]
	v_pk_mul_f32 v[64:65], v[64:65], v[166:167]
	v_pk_mul_f32 v[60:61], v[60:61], v[174:175]
	v_pk_mul_f32 v[56:57], v[56:57], v[226:227]
	v_pk_mul_f32 v[52:53], v[52:53], v[230:231]
	v_pk_mul_f32 v[50:51], v[50:51], v[228:229]
	v_pk_mul_f32 v[46:47], v[46:47], v[164:165]
	v_pk_mul_f32 v[42:43], v[42:43], v[172:173]
	v_pk_mul_f32 v[38:39], v[38:39], v[224:225]
	v_pk_mul_f32 v[48:49], v[48:49], v[166:167]
	v_pk_mul_f32 v[44:45], v[44:45], v[174:175]
	v_pk_mul_f32 v[40:41], v[40:41], v[226:227]
	v_pk_mul_f32 v[36:37], v[36:37], v[230:231]
	v_pk_mul_f32 v[34:35], v[34:35], v[228:229]
	v_pk_mul_f32 v[30:31], v[30:31], v[164:165]
	v_pk_mul_f32 v[26:27], v[26:27], v[172:173]
	v_pk_mul_f32 v[22:23], v[22:23], v[224:225]
	v_pk_mul_f32 v[32:33], v[32:33], v[166:167]
	v_pk_mul_f32 v[28:29], v[28:29], v[174:175]
	v_pk_mul_f32 v[24:25], v[24:25], v[226:227]
	v_pk_mul_f32 v[20:21], v[20:21], v[230:231]
	v_pk_mul_f32 v[18:19], v[18:19], v[228:229]

; #define SBAR() __builtin_amdgcn_sched_barrier(0)
; __device__ __forceinline__ void partialSM(f32x16& p0, f32x16& p1, float& m_reg, float& mn, float& alpha) {
;     ...
;   float pmax = p0[0]; for (int r = 1; r < 16; ++r) pmax = fmaxf(pmax, p0[r]); for (int r = 0; r < 16; ++r) pmax = fmaxf(pmax, p1[r]);
;   { auto rr = __builtin_amdgcn_permlane32_swap(__float_as_uint(pmax), __float_as_uint(pmax), false, false);
;     pmax = fmaxf(__uint_as_float(rr[0]), __uint_as_float(rr[1])); }
;   if (__builtin_expect(__all(pmax - m_reg <= THR / SCALE), 1)) { mn = m_reg; alpha = 1.f; }
;   else { mn = fmaxf(m_reg, pmax); alpha = __builtin_amdgcn_exp2f((m_reg - mn) * C); m_reg = mn; }
; template <int OFF> __device__ __forceinline__ s16x4 tr_read(int vb) {
;   s16x4 r; asm volatile("ds_read_b64_tr_b16 %0, %1 offset:%2" : "=&v"(r) : "v"(vb), "i"(OFF) : "memory"); return r;
; }
; template <int D0> __device__ __forceinline__ void pv_one(f32x16& od, int vb, bf16x8 pa0, bf16x8 pa1, bf16x8 pa2, bf16x8 pa3) {
;   const s16x4 l0 = tr_read<v_rd_off(D0, 0, 0)>(vb), h0 = tr_read<v_rd_off(D0, 0, 1)>(vb), l1 = tr_read<v_rd_off(D0, 1, 0)>(vb), h1 = tr_read<v_rd_off(D0, 1, 1)>(vb);
;   const s16x4 l2 = tr_read<v_rd_off(D0, 2, 0)>(vb), h2 = tr_read<v_rd_off(D0, 2, 1)>(vb), l3 = tr_read<v_rd_off(D0, 3, 0)>(vb), h3 = tr_read<v_rd_off(D0, 3, 1)>(vb);
;   asm volatile("s_waitcnt lgkmcnt(0)" ::: "memory"); SBAR();
;     ...
;   od = __builtin_amdgcn_mfma_f32_32x32x16_bf16(pa0, PK(l0, h0), od, 0, 0, 0);
;   od = __builtin_amdgcn_mfma_f32_32x32x16_bf16(pa1, PK(l1, h1), od, 0, 0, 0);
;   od = __builtin_amdgcn_mfma_f32_32x32x16_bf16(pa2, PK(l2, h2), od, 0, 0, 0);
;   od = __builtin_amdgcn_mfma_f32_32x32x16_bf16(pa3, PK(l3, h3), od, 0, 0, 0);
;     ...
; }
; __device__ __forceinline__ void pv_d0(f32x16* o, int vb, bf16x8 pa0, bf16x8 pa1, bf16x8 pa2, bf16x8 pa3) {
;   pv_one<0>(o[0], vb, pa0, pa1, pa2, pa3); pv_one<1>(o[1], vb, pa0, pa1, pa2, pa3); pv_one<2>(o[2], vb, pa0, pa1, pa2, pa3); pv_one<3>(o[3], vb, pa0, pa1, pa2, pa3);
.LBB0_186:
	ds_read_b64_tr_b16 v[228:229], v187 offset:0
	ds_read_b64_tr_b16 v[230:231], v187 offset:0x800
	ds_read_b64_tr_b16 v[232:233], v187 offset:0x1000
	ds_read_b64_tr_b16 v[234:235], v187 offset:0x1800
	ds_read_b64_tr_b16 v[236:237], v187 offset:0x2000
	ds_read_b64_tr_b16 v[238:239], v187 offset:0x2800
	ds_read_b64_tr_b16 v[240:241], v187 offset:0x3000
	ds_read_b64_tr_b16 v[242:243], v187 offset:0x3800
	s_nop 0
	s_waitcnt lgkmcnt(6)
	v_mfma_f32_32x32x16_bf16 v[2:17], v[162:165], v[228:231], v[2:17]
	ds_read_b64_tr_b16 v[228:229], v187 offset:0x200
	ds_read_b64_tr_b16 v[230:231], v187 offset:0xa00
	s_waitcnt lgkmcnt(6)
	v_mfma_f32_32x32x16_bf16 v[2:17], v[166:169], v[232:235], v[2:17]
	ds_read_b64_tr_b16 v[232:233], v187 offset:0x1200
	ds_read_b64_tr_b16 v[234:235], v187 offset:0x1a00
	s_waitcnt lgkmcnt(6)
	v_mfma_f32_32x32x16_bf16 v[2:17], v[170:173], v[236:239], v[2:17]
	ds_read_b64_tr_b16 v[236:237], v187 offset:0x2200
	ds_read_b64_tr_b16 v[238:239], v187 offset:0x2a00
	s_waitcnt lgkmcnt(6)
	v_mfma_f32_32x32x16_bf16 v[2:17], v[174:177], v[240:243], v[2:17]
	ds_read_b64_tr_b16 v[240:241], v187 offset:0x3200
	ds_read_b64_tr_b16 v[242:243], v187 offset:0x3a00
	s_waitcnt lgkmcnt(6)
	v_mfma_f32_32x32x16_bf16 v[50:65], v[162:165], v[228:231], v[50:65]
	ds_read_b64_tr_b16 v[228:229], v187 offset:0x400
	ds_read_b64_tr_b16 v[230:231], v187 offset:0xc00
	s_waitcnt lgkmcnt(6)
	v_mfma_f32_32x32x16_bf16 v[50:65], v[166:169], v[232:235], v[50:65]
	ds_read_b64_tr_b16 v[232:233], v187 offset:0x1400
	ds_read_b64_tr_b16 v[234:235], v187 offset:0x1c00
	s_waitcnt lgkmcnt(6)
	v_mfma_f32_32x32x16_bf16 v[50:65], v[170:173], v[236:239], v[50:65]
	ds_read_b64_tr_b16 v[236:237], v187 offset:0x2400
	ds_read_b64_tr_b16 v[238:239], v187 offset:0x2c00
	s_waitcnt lgkmcnt(6)
	v_mfma_f32_32x32x16_bf16 v[50:65], v[174:177], v[240:243], v[50:65]
	ds_read_b64_tr_b16 v[240:241], v187 offset:0x3400
	ds_read_b64_tr_b16 v[242:243], v187 offset:0x3c00
	s_waitcnt lgkmcnt(6)
	v_mfma_f32_32x32x16_bf16 v[34:49], v[162:165], v[228:231], v[34:49]
	ds_read_b64_tr_b16 v[228:229], v187 offset:0x600
	ds_read_b64_tr_b16 v[230:231], v187 offset:0xe00
	s_waitcnt lgkmcnt(6)
	v_mfma_f32_32x32x16_bf16 v[34:49], v[166:169], v[232:235], v[34:49]
	ds_read_b64_tr_b16 v[232:233], v187 offset:0x1600
	ds_read_b64_tr_b16 v[234:235], v187 offset:0x1e00
	s_waitcnt lgkmcnt(6)
	v_mfma_f32_32x32x16_bf16 v[34:49], v[170:173], v[236:239], v[34:49]
	ds_read_b64_tr_b16 v[236:237], v187 offset:0x2600
	ds_read_b64_tr_b16 v[238:239], v187 offset:0x2e00
	s_waitcnt lgkmcnt(6)
	v_mfma_f32_32x32x16_bf16 v[34:49], v[174:177], v[240:243], v[34:49]
	ds_read_b64_tr_b16 v[240:241], v187 offset:0x3600
	ds_read_b64_tr_b16 v[242:243], v187 offset:0x3e00
	s_waitcnt lgkmcnt(6)
	v_mfma_f32_32x32x16_bf16 v[18:33], v[162:165], v[228:231], v[18:33]
	v_max_f32_e32 v162, v83, v83
	v_max_f32_e32 v163, v82, v82
	v_max_f32_e32 v162, v163, v162
	v_max3_f32 v162, v162, v84, v85
	v_max3_f32 v162, v162, v86, v87
	v_max3_f32 v162, v162, v88, v89
	v_max3_f32 v162, v162, v90, v91
	v_max3_f32 v162, v162, v92, v93
	v_max3_f32 v162, v162, v94, v95
	s_waitcnt lgkmcnt(4)
	v_mfma_f32_32x32x16_bf16 v[18:33], v[166:169], v[232:235], v[18:33]
	v_max3_f32 v162, v162, v96, v97
	v_max3_f32 v162, v162, v66, v67
	v_max3_f32 v162, v162, v68, v69
	v_max3_f32 v162, v162, v70, v71
	v_max3_f32 v162, v162, v72, v73
	v_max3_f32 v162, v162, v74, v75
	v_max3_f32 v162, v162, v76, v77
	v_max3_f32 v162, v162, v78, v79
	s_waitcnt lgkmcnt(2)
	v_mfma_f32_32x32x16_bf16 v[18:33], v[170:173], v[236:239], v[18:33]
	v_max3_f32 v162, v162, v80, v81
	v_mov_b32_e32 v163, v162
	s_nop 1
	v_permlane32_swap_b32_e32 v162, v163
	v_max_f32_e32 v163, v163, v163
	v_max_f32_e32 v162, v162, v162
	v_max_f32_e32 v162, v162, v163
	v_sub_f32_e32 v163, v162, v224
	v_cmp_ge_f32_e32 vcc, s27, v163
	v_max_f32_e32 v163, v224, v224
	v_max_f32_e32 v163, v163, v162
	s_waitcnt lgkmcnt(0)
	v_mfma_f32_32x32x16_bf16 v[18:33], v[174:177], v[240:243], v[18:33]
	v_sub_f32_e32 v162, v224, v163
	v_mul_f32_e32 v162, 0x3e0293ee, v162
	v_exp_f32_e32 v162, v162
	s_cmp_eq_u64 vcc, exec
	s_cselect_b64 s[0:1], -1, 0
	s_barrier
	s_waitcnt vmcnt(4)
	v_cndmask_b32_e64 v162, v162, 1.0, s[0:1]
	v_cmp_gt_f32_e32 vcc, 1.0, v162
	s_waitcnt vmcnt(3)
	ds_write_b128 v210, v[146:149] offset:16384
	s_waitcnt vmcnt(2)
	ds_write_b128 v211, v[150:153] offset:16384
	s_waitcnt vmcnt(1)
	ds_write_b128 v208, v[154:157] offset:49152
	s_waitcnt vmcnt(0)
	ds_write_b128 v209, v[158:161] offset:49152
	s_cbranch_vccz .LBB0_190
	s_and_saveexec_b64 s[46:47], s[40:41]
	ds_write_b32 v185, v162 offset:128
	s_or_b64 exec, exec, s[46:47]
	s_waitcnt lgkmcnt(0)
	v_add_u32_e32 v158, v181, v0
	ds_read_b128 v[146:149], v158 offset:224
	ds_read_b128 v[150:153], v158 offset:192
	ds_read_b128 v[154:157], v158 offset:160
	ds_read_b128 v[158:161], v158 offset:128
	s_waitcnt lgkmcnt(3)
	v_pk_mul_f32 v[14:15], v[14:15], v[146:147]
	s_waitcnt lgkmcnt(2)
	v_pk_mul_f32 v[10:11], v[10:11], v[150:151]
	s_waitcnt lgkmcnt(1)
	v_pk_mul_f32 v[6:7], v[6:7], v[154:155]
	v_pk_mul_f32 v[16:17], v[16:17], v[148:149]
	v_pk_mul_f32 v[12:13], v[12:13], v[152:153]
	v_pk_mul_f32 v[8:9], v[8:9], v[156:157]
	s_waitcnt lgkmcnt(0)
	v_pk_mul_f32 v[4:5], v[4:5], v[160:161]
	v_pk_mul_f32 v[2:3], v[2:3], v[158:159]
	v_pk_mul_f32 v[62:63], v[62:63], v[146:147]
	v_pk_mul_f32 v[58:59], v[58:59], v[150:151]
	v_pk_mul_f32 v[54:55], v[54:55], v[154:155]
	v_pk_mul_f32 v[64:65], v[64:65], v[148:149]
	v_pk_mul_f32 v[60:61], v[60:61], v[152:153]
	v_pk_mul_f32 v[56:57], v[56:57], v[156:157]
	v_pk_mul_f32 v[52:53], v[52:53], v[160:161]
	v_pk_mul_f32 v[50:51], v[50:51], v[158:159]
	v_pk_mul_f32 v[46:47], v[46:47], v[146:147]
	v_pk_mul_f32 v[42:43], v[42:43], v[150:151]
	v_pk_mul_f32 v[38:39], v[38:39], v[154:155]
	v_pk_mul_f32 v[48:49], v[48:49], v[148:149]
	v_pk_mul_f32 v[44:45], v[44:45], v[152:153]
	v_pk_mul_f32 v[40:41], v[40:41], v[156:157]
	v_pk_mul_f32 v[36:37], v[36:37], v[160:161]
	v_pk_mul_f32 v[34:35], v[34:35], v[158:159]
	v_pk_mul_f32 v[30:31], v[30:31], v[146:147]
	v_pk_mul_f32 v[26:27], v[26:27], v[150:151]
	v_pk_mul_f32 v[22:23], v[22:23], v[154:155]
	v_pk_mul_f32 v[32:33], v[32:33], v[148:149]
	v_pk_mul_f32 v[28:29], v[28:29], v[152:153]
	v_pk_mul_f32 v[24:25], v[24:25], v[156:157]
	v_pk_mul_f32 v[20:21], v[20:21], v[160:161]
	v_pk_mul_f32 v[18:19], v[18:19], v[158:159]
